# speedup vs baseline: 1.0003x; 1.0003x over previous
; #define LDSP(TY, p) ((__attribute__((address_space(3))) TY*)(p))
; __device__ __forceinline__ void ph_gmlp(const Params& p, int l, char* shm) {
;     ...
;     {
;       const u16* up = p.P + t * NP + U_OFF + g * 128 + g4 * 4;
;       const u16* gp = p.P + t * NP + GB_OFF + g * 128 + g4 * 4;
; #pragma unroll
;       for (int nt = 0; nt < 8; ++nt) { uu[nt] = *(const uint2*)(up + nt * 16); gg[nt] = *(const uint2*)(gp + nt * 16); }
;     }
;     const float bias = p.b_s[(l * 16 + g) * 128 + i];
;     {
;       const int r = tid >> 2, q = tid & 3;
;       const uint4* src = (const uint4*)(p.P + (tok0 + r) * NP + V_OFF + g * 128 + q * 32);
; #pragma unroll
;       for (int k = 0; k < 4; ++k) *(uint4*)(shm + r * 272 + q * 64 + k * 16) = src[k];
;     }
;     __syncthreads();
;     f32x4 acc[8];
; #pragma unroll
;     for (int nt = 0; nt < 8; ++nt) acc[nt] = f32x4{0.f, 0.f, 0.f, 0.f};
;     const u16* wsb = p.ws + ((size_t)(l * 16 + g) * 128 + wid * 16 + m) * 128 + g4 * 4;
;     const int rdbase = (g4 * 4 + (m >> 2)) * 272 + (m & 3) * 8;
;     for (int ks = 0; ks <= wid; ++ks) {
;       const s16x4 a = *(const s16x4*)(wsb + ks * 16);
; #pragma unroll
;       for (int nt = 0; nt < 8; ++nt) {
;         const s16x4 bb = __builtin_amdgcn_ds_read_tr16_b64_v4i16(LDSP(s16x4, shm + rdbase + ks * 16 * 272 + nt * 32));
;         acc[nt] = __builtin_amdgcn_mfma_f32_16x16x16bf16_1k(bb, a, acc[nt], 0, 0, 0);
;       }
;     }
.LBB0_950:
	s_ashr_i32 s2, s9, 4
	s_ashr_i32 s3, s2, 31
	s_lshl_b64 s[2:3], s[2:3], 7
	v_lshl_add_u64 v[72:73], s[2:3], 0, v[34:35]
	v_mov_b64_e32 v[0:1], s[26:27]
	s_movk_i32 s4, 0x7600
	s_and_b32 s10, s9, 15
	v_mad_u64_u32 v[2:3], s[12:13], v72, s4, v[0:1]
	v_mad_i32_i24 v3, v73, s4, v3
	s_lshl_b32 s4, s10, 8
	v_lshl_add_u64 v[2:3], v[2:3], 0, s[4:5]
	v_lshl_add_u64 v[2:3], v[2:3], 0, v[32:33]
	s_movk_i32 s11, 0x4000
	s_mov_b64 s[12:13], 0x4600
	v_add_co_u32_e32 v8, vcc, s11, v2
	v_lshl_add_u64 v[4:5], v[2:3], 0, s[12:13]
	s_mov_b64 s[12:13], 0x6600
	v_addc_co_u32_e32 v9, vcc, 0, v3, vcc
	s_movk_i32 s11, 0x6000
	v_lshl_add_u64 v[6:7], v[2:3], 0, s[12:13]
	v_add_co_u32_e32 v2, vcc, s11, v2
	s_or_b32 s11, s10, s6
	s_nop 0
	v_addc_co_u32_e32 v3, vcc, 0, v3, vcc
	global_load_dwordx2 v[74:75], v[8:9], off offset:1536
	global_load_dwordx2 v[76:77], v[2:3], off offset:1536
	global_load_dwordx2 v[68:69], v[4:5], off offset:32
	global_load_dwordx2 v[70:71], v[6:7], off offset:32
	global_load_dwordx2 v[64:65], v[4:5], off offset:64
	global_load_dwordx2 v[66:67], v[6:7], off offset:64
	global_load_dwordx2 v[60:61], v[4:5], off offset:96
	global_load_dwordx2 v[62:63], v[6:7], off offset:96
	global_load_dwordx2 v[56:57], v[4:5], off offset:128
	global_load_dwordx2 v[58:59], v[6:7], off offset:128
	global_load_dwordx2 v[52:53], v[4:5], off offset:160
	global_load_dwordx2 v[54:55], v[6:7], off offset:160
	global_load_dwordx2 v[48:49], v[4:5], off offset:192
	global_load_dwordx2 v[50:51], v[6:7], off offset:192
	global_load_dwordx2 v[42:43], v[4:5], off offset:224
	global_load_dwordx2 v[44:45], v[6:7], off offset:224
	v_lshl_add_u32 v2, s11, 7, v34
	v_readlane_b32 s16, v246, 4
	v_ashrrev_i32_e32 v3, 31, v2
	v_readlane_b32 s22, v246, 10
	v_readlane_b32 s23, v246, 11
	s_movk_i32 s11, 0x7600
	v_mov_b32_e32 v41, v33
	v_lshl_add_u64 v[2:3], v[2:3], 2, s[22:23]
	global_load_dword v46, v[2:3], off
	v_lshl_add_u64 v[2:3], s[2:3], 0, v[36:37]
	v_mad_u64_u32 v[0:1], s[2:3], v2, s11, v[0:1]
	v_mad_i32_i24 v1, v3, s11, v1
	v_lshl_add_u64 v[0:1], v[0:1], 0, s[4:5]
	v_lshl_add_u64 v[0:1], v[0:1], 0, v[40:41]
	s_mov_b64 s[2:3], 0x5600
	v_lshl_add_u64 v[4:5], v[0:1], 0, s[2:3]
	s_movk_i32 s2, 0x5000
	v_add_co_u32_e32 v0, vcc, s2, v0
	v_readlane_b32 s17, v246, 5
	s_nop 0
	v_addc_co_u32_e32 v1, vcc, 0, v1, vcc
	global_load_dwordx4 v[88:91], v[0:1], off offset:1536
	global_load_dwordx4 v[92:95], v[4:5], off offset:16
	global_load_dwordx4 v[96:99], v[4:5], off offset:32
	global_load_dwordx4 v[100:103], v[4:5], off offset:48
	s_and_b32 s2, s8, 15
	s_add_i32 s2, s6, s2
	s_ashr_i32 s3, s2, 31
	s_lshl_b64 s[2:3], s[2:3], 15
	v_lshl_add_u64 v[78:79], v[38:39], 0, s[2:3]
	global_load_dwordx2 v[104:105], v[78:79], off
	global_load_dwordx2 v[106:107], v[78:79], off offset:32
	global_load_dwordx2 v[108:109], v[78:79], off offset:64
	global_load_dwordx2 v[110:111], v[78:79], off offset:96
	global_load_dwordx2 v[112:113], v[78:79], off offset:128
	global_load_dwordx2 v[114:115], v[78:79], off offset:160
	global_load_dwordx2 v[116:117], v[78:79], off offset:192
	global_load_dwordx2 v[118:119], v[78:79], off offset:224
	s_andn2_b64 vcc, exec, s[0:1]
	v_readlane_b32 s18, v246, 6
	v_readlane_b32 s19, v246, 7
	v_readlane_b32 s20, v246, 8
	v_readlane_b32 s21, v246, 9
	v_readlane_b32 s24, v246, 12
	v_readlane_b32 s25, v246, 13
	v_readlane_b32 s26, v246, 14
	v_readlane_b32 s27, v246, 15
	v_readlane_b32 s28, v246, 16
	v_readlane_b32 s29, v246, 17
	v_readlane_b32 s30, v246, 18
	v_readlane_b32 s31, v246, 19
	s_waitcnt vmcnt(8)
	ds_write_b128 v47, v[88:91]
	ds_write_b128 v80, v[92:95]
	ds_write_b128 v81, v[96:99]
	ds_write_b128 v82, v[100:103]
	v_mov_b32_e32 v3, 0
	v_mov_b32_e32 v2, v3
	v_mov_b32_e32 v1, v3
	v_mov_b32_e32 v0, v3
	v_mov_b32_e32 v7, v3
	v_mov_b32_e32 v6, v3
	v_mov_b32_e32 v5, v3
	v_mov_b32_e32 v4, v3
	v_mov_b32_e32 v11, v3
	v_mov_b32_e32 v10, v3
	v_mov_b32_e32 v9, v3
	v_mov_b32_e32 v8, v3
	v_mov_b32_e32 v15, v3
	v_mov_b32_e32 v14, v3
	v_mov_b32_e32 v13, v3
	v_mov_b32_e32 v12, v3
	v_mov_b32_e32 v19, v3
	v_mov_b32_e32 v18, v3
	v_mov_b32_e32 v17, v3
	v_mov_b32_e32 v16, v3
	v_mov_b32_e32 v23, v3
	v_mov_b32_e32 v22, v3
	v_mov_b32_e32 v21, v3
	v_mov_b32_e32 v20, v3
	v_mov_b32_e32 v27, v3
	v_mov_b32_e32 v26, v3
	v_mov_b32_e32 v25, v3
	v_mov_b32_e32 v24, v3
	v_mov_b32_e32 v31, v3
	v_mov_b32_e32 v30, v3
	v_mov_b32_e32 v29, v3
	v_mov_b32_e32 v28, v3
	s_waitcnt lgkmcnt(0)
	s_barrier
	s_cbranch_vccnz .LBB0_949
	v_mov_b32_e32 v0, 0
	v_mov_b32_e32 v1, v0
	v_mov_b32_e32 v2, v0
	v_mov_b32_e32 v3, v0
	v_mov_b32_e32 v28, v0
	v_mov_b32_e32 v29, v0
	v_mov_b32_e32 v30, v0
	v_mov_b32_e32 v31, v0
	v_mov_b32_e32 v24, v0
	v_mov_b32_e32 v25, v0
	v_mov_b32_e32 v26, v0
	v_mov_b32_e32 v27, v0
	v_mov_b32_e32 v20, v0
	v_mov_b32_e32 v21, v0
	v_mov_b32_e32 v22, v0
	v_mov_b32_e32 v23, v0
	v_mov_b32_e32 v16, v0
	v_mov_b32_e32 v17, v0
	v_mov_b32_e32 v18, v0
	v_mov_b32_e32 v19, v0
	v_mov_b32_e32 v12, v0
	v_mov_b32_e32 v13, v0
	v_mov_b32_e32 v14, v0
	v_mov_b32_e32 v15, v0
	v_mov_b32_e32 v8, v0
	v_mov_b32_e32 v9, v0
	v_mov_b32_e32 v10, v0
	v_mov_b32_e32 v11, v0
	v_mov_b32_e32 v4, v0
	v_mov_b32_e32 v5, v0
	v_mov_b32_e32 v6, v0
	v_mov_b32_e32 v7, v0
	v_add_u32_e32 v120, 0xffffff20, v83
	s_mov_b32 s2, s7
	ds_read_b64_tr_b16 v[122:123], v120
	ds_read_b64_tr_b16 v[124:125], v120 offset:32
	ds_read_b64_tr_b16 v[126:127], v120 offset:64
	ds_read_b64_tr_b16 v[128:129], v120 offset:96
	ds_read_b64_tr_b16 v[130:131], v120 offset:128
	ds_read_b64_tr_b16 v[132:133], v120 offset:160
	ds_read_b64_tr_b16 v[134:135], v120 offset:192
	ds_read_b64_tr_b16 v[136:137], v120 offset:224
	s_waitcnt vmcnt(7)
	s_waitcnt lgkmcnt(7)
	v_mfma_f32_16x16x16_bf16 v[28:31], v[122:123], v[104:105], v[28:31]
	s_waitcnt lgkmcnt(6)
	v_mfma_f32_16x16x16_bf16 v[24:27], v[124:125], v[104:105], v[24:27]
	s_waitcnt lgkmcnt(5)
	v_mfma_f32_16x16x16_bf16 v[20:23], v[126:127], v[104:105], v[20:23]
	s_waitcnt lgkmcnt(4)
	v_mfma_f32_16x16x16_bf16 v[16:19], v[128:129], v[104:105], v[16:19]
	s_waitcnt lgkmcnt(3)
	v_mfma_f32_16x16x16_bf16 v[12:15], v[130:131], v[104:105], v[12:15]
	s_waitcnt lgkmcnt(2)
	v_mfma_f32_16x16x16_bf16 v[8:11], v[132:133], v[104:105], v[8:11]
	s_waitcnt lgkmcnt(1)
	v_mfma_f32_16x16x16_bf16 v[4:7], v[134:135], v[104:105], v[4:7]
	s_waitcnt lgkmcnt(0)
	v_mfma_f32_16x16x16_bf16 v[0:3], v[136:137], v[104:105], v[0:3]
	s_cmp_eq_u32 s2, 1
	s_cbranch_scc1 .LBB0_949
; #define LDSP(TY, p) ((__attribute__((address_space(3))) TY*)(p))
; __device__ __forceinline__ void ph_gmlp(const Params& p, int l, char* shm) {
;     ...
;     for (int ks = 0; ks <= wid; ++ks) {
;       const s16x4 a = *(const s16x4*)(wsb + ks * 16);
; #pragma unroll
;       for (int nt = 0; nt < 8; ++nt) {
;         const s16x4 bb = __builtin_amdgcn_ds_read_tr16_b64_v4i16(LDSP(s16x4, shm + rdbase + ks * 16 * 272 + nt * 32));
;         acc[nt] = __builtin_amdgcn_mfma_f32_16x16x16bf16_1k(bb, a, acc[nt], 0, 0, 0);
;       }
;     }
	ds_read_b64_tr_b16 v[122:123], v120 offset:4352
	ds_read_b64_tr_b16 v[124:125], v120 offset:4384
	ds_read_b64_tr_b16 v[126:127], v120 offset:4416
	ds_read_b64_tr_b16 v[128:129], v120 offset:4448
	ds_read_b64_tr_b16 v[130:131], v120 offset:4480
	ds_read_b64_tr_b16 v[132:133], v120 offset:4512
	ds_read_b64_tr_b16 v[134:135], v120 offset:4544
	ds_read_b64_tr_b16 v[136:137], v120 offset:4576
	s_waitcnt vmcnt(6)
	s_waitcnt lgkmcnt(7)
	v_mfma_f32_16x16x16_bf16 v[28:31], v[122:123], v[106:107], v[28:31]
	s_waitcnt lgkmcnt(6)
	v_mfma_f32_16x16x16_bf16 v[24:27], v[124:125], v[106:107], v[24:27]
	s_waitcnt lgkmcnt(5)
	v_mfma_f32_16x16x16_bf16 v[20:23], v[126:127], v[106:107], v[20:23]
	s_waitcnt lgkmcnt(4)
	v_mfma_f32_16x16x16_bf16 v[16:19], v[128:129], v[106:107], v[16:19]
	s_waitcnt lgkmcnt(3)
	v_mfma_f32_16x16x16_bf16 v[12:15], v[130:131], v[106:107], v[12:15]
	s_waitcnt lgkmcnt(2)
	v_mfma_f32_16x16x16_bf16 v[8:11], v[132:133], v[106:107], v[8:11]
	s_waitcnt lgkmcnt(1)
	v_mfma_f32_16x16x16_bf16 v[4:7], v[134:135], v[106:107], v[4:7]
	s_waitcnt lgkmcnt(0)
	v_mfma_f32_16x16x16_bf16 v[0:3], v[136:137], v[106:107], v[0:3]
	s_cmp_eq_u32 s2, 2
	s_cbranch_scc1 .LBB0_949
	ds_read_b64_tr_b16 v[122:123], v120 offset:8704
	ds_read_b64_tr_b16 v[124:125], v120 offset:8736
	ds_read_b64_tr_b16 v[126:127], v120 offset:8768
	ds_read_b64_tr_b16 v[128:129], v120 offset:8800
	ds_read_b64_tr_b16 v[130:131], v120 offset:8832
	ds_read_b64_tr_b16 v[132:133], v120 offset:8864
	ds_read_b64_tr_b16 v[134:135], v120 offset:8896
	ds_read_b64_tr_b16 v[136:137], v120 offset:8928
	s_waitcnt vmcnt(5)
	s_waitcnt lgkmcnt(7)
	v_mfma_f32_16x16x16_bf16 v[28:31], v[122:123], v[108:109], v[28:31]
	s_waitcnt lgkmcnt(6)
	v_mfma_f32_16x16x16_bf16 v[24:27], v[124:125], v[108:109], v[24:27]
	s_waitcnt lgkmcnt(5)
	v_mfma_f32_16x16x16_bf16 v[20:23], v[126:127], v[108:109], v[20:23]
	s_waitcnt lgkmcnt(4)
	v_mfma_f32_16x16x16_bf16 v[16:19], v[128:129], v[108:109], v[16:19]
	s_waitcnt lgkmcnt(3)
	v_mfma_f32_16x16x16_bf16 v[12:15], v[130:131], v[108:109], v[12:15]
	s_waitcnt lgkmcnt(2)
	v_mfma_f32_16x16x16_bf16 v[8:11], v[132:133], v[108:109], v[8:11]
	s_waitcnt lgkmcnt(1)
	v_mfma_f32_16x16x16_bf16 v[4:7], v[134:135], v[108:109], v[4:7]
	s_waitcnt lgkmcnt(0)
	v_mfma_f32_16x16x16_bf16 v[0:3], v[136:137], v[108:109], v[0:3]
	s_cmp_eq_u32 s2, 3
	s_cbranch_scc1 .LBB0_949
	ds_read_b64_tr_b16 v[122:123], v120 offset:13056
	ds_read_b64_tr_b16 v[124:125], v120 offset:13088
	ds_read_b64_tr_b16 v[126:127], v120 offset:13120
	ds_read_b64_tr_b16 v[128:129], v120 offset:13152
	ds_read_b64_tr_b16 v[130:131], v120 offset:13184
	ds_read_b64_tr_b16 v[132:133], v120 offset:13216
	ds_read_b64_tr_b16 v[134:135], v120 offset:13248
	ds_read_b64_tr_b16 v[136:137], v120 offset:13280
	s_waitcnt vmcnt(4)
	s_waitcnt lgkmcnt(7)
	v_mfma_f32_16x16x16_bf16 v[28:31], v[122:123], v[110:111], v[28:31]
	s_waitcnt lgkmcnt(6)
	v_mfma_f32_16x16x16_bf16 v[24:27], v[124:125], v[110:111], v[24:27]
	s_waitcnt lgkmcnt(5)
	v_mfma_f32_16x16x16_bf16 v[20:23], v[126:127], v[110:111], v[20:23]
	s_waitcnt lgkmcnt(4)
	v_mfma_f32_16x16x16_bf16 v[16:19], v[128:129], v[110:111], v[16:19]
	s_waitcnt lgkmcnt(3)
	v_mfma_f32_16x16x16_bf16 v[12:15], v[130:131], v[110:111], v[12:15]
	s_waitcnt lgkmcnt(2)
	v_mfma_f32_16x16x16_bf16 v[8:11], v[132:133], v[110:111], v[8:11]
	s_waitcnt lgkmcnt(1)
	v_mfma_f32_16x16x16_bf16 v[4:7], v[134:135], v[110:111], v[4:7]
	s_waitcnt lgkmcnt(0)
	v_mfma_f32_16x16x16_bf16 v[0:3], v[136:137], v[110:111], v[0:3]
	s_cmp_eq_u32 s2, 4
	s_cbranch_scc1 .LBB0_949
; #define LDSP(TY, p) ((__attribute__((address_space(3))) TY*)(p))
; __device__ __forceinline__ void ph_gmlp(const Params& p, int l, char* shm) {
;     ...
;     for (int ks = 0; ks <= wid; ++ks) {
;       const s16x4 a = *(const s16x4*)(wsb + ks * 16);
; #pragma unroll
;       for (int nt = 0; nt < 8; ++nt) {
;         const s16x4 bb = __builtin_amdgcn_ds_read_tr16_b64_v4i16(LDSP(s16x4, shm + rdbase + ks * 16 * 272 + nt * 32));
;         acc[nt] = __builtin_amdgcn_mfma_f32_16x16x16bf16_1k(bb, a, acc[nt], 0, 0, 0);
;       }
;     }
	ds_read_b64_tr_b16 v[122:123], v120 offset:17408
	ds_read_b64_tr_b16 v[124:125], v120 offset:17440
	ds_read_b64_tr_b16 v[126:127], v120 offset:17472
	ds_read_b64_tr_b16 v[128:129], v120 offset:17504
	ds_read_b64_tr_b16 v[130:131], v120 offset:17536
	ds_read_b64_tr_b16 v[132:133], v120 offset:17568
	ds_read_b64_tr_b16 v[134:135], v120 offset:17600
	ds_read_b64_tr_b16 v[136:137], v120 offset:17632
	s_waitcnt vmcnt(3)
	s_waitcnt lgkmcnt(7)
	v_mfma_f32_16x16x16_bf16 v[28:31], v[122:123], v[112:113], v[28:31]
	s_waitcnt lgkmcnt(6)
	v_mfma_f32_16x16x16_bf16 v[24:27], v[124:125], v[112:113], v[24:27]
	s_waitcnt lgkmcnt(5)
	v_mfma_f32_16x16x16_bf16 v[20:23], v[126:127], v[112:113], v[20:23]
	s_waitcnt lgkmcnt(4)
	v_mfma_f32_16x16x16_bf16 v[16:19], v[128:129], v[112:113], v[16:19]
	s_waitcnt lgkmcnt(3)
	v_mfma_f32_16x16x16_bf16 v[12:15], v[130:131], v[112:113], v[12:15]
	s_waitcnt lgkmcnt(2)
	v_mfma_f32_16x16x16_bf16 v[8:11], v[132:133], v[112:113], v[8:11]
	s_waitcnt lgkmcnt(1)
	v_mfma_f32_16x16x16_bf16 v[4:7], v[134:135], v[112:113], v[4:7]
	s_waitcnt lgkmcnt(0)
	v_mfma_f32_16x16x16_bf16 v[0:3], v[136:137], v[112:113], v[0:3]
	s_cmp_eq_u32 s2, 5
	s_cbranch_scc1 .LBB0_949
	ds_read_b64_tr_b16 v[122:123], v120 offset:21760
	ds_read_b64_tr_b16 v[124:125], v120 offset:21792
	ds_read_b64_tr_b16 v[126:127], v120 offset:21824
	ds_read_b64_tr_b16 v[128:129], v120 offset:21856
	ds_read_b64_tr_b16 v[130:131], v120 offset:21888
	ds_read_b64_tr_b16 v[132:133], v120 offset:21920
	ds_read_b64_tr_b16 v[134:135], v120 offset:21952
	ds_read_b64_tr_b16 v[136:137], v120 offset:21984
	s_waitcnt vmcnt(2)
	s_waitcnt lgkmcnt(7)
	v_mfma_f32_16x16x16_bf16 v[28:31], v[122:123], v[114:115], v[28:31]
	s_waitcnt lgkmcnt(6)
	v_mfma_f32_16x16x16_bf16 v[24:27], v[124:125], v[114:115], v[24:27]
	s_waitcnt lgkmcnt(5)
	v_mfma_f32_16x16x16_bf16 v[20:23], v[126:127], v[114:115], v[20:23]
	s_waitcnt lgkmcnt(4)
	v_mfma_f32_16x16x16_bf16 v[16:19], v[128:129], v[114:115], v[16:19]
	s_waitcnt lgkmcnt(3)
	v_mfma_f32_16x16x16_bf16 v[12:15], v[130:131], v[114:115], v[12:15]
	s_waitcnt lgkmcnt(2)
	v_mfma_f32_16x16x16_bf16 v[8:11], v[132:133], v[114:115], v[8:11]
	s_waitcnt lgkmcnt(1)
	v_mfma_f32_16x16x16_bf16 v[4:7], v[134:135], v[114:115], v[4:7]
	s_waitcnt lgkmcnt(0)
	v_mfma_f32_16x16x16_bf16 v[0:3], v[136:137], v[114:115], v[0:3]
	s_cmp_eq_u32 s2, 6
	s_cbranch_scc1 .LBB0_949
	ds_read_b64_tr_b16 v[122:123], v120 offset:26112
	ds_read_b64_tr_b16 v[124:125], v120 offset:26144
	ds_read_b64_tr_b16 v[126:127], v120 offset:26176
	ds_read_b64_tr_b16 v[128:129], v120 offset:26208
	ds_read_b64_tr_b16 v[130:131], v120 offset:26240
	ds_read_b64_tr_b16 v[132:133], v120 offset:26272
	ds_read_b64_tr_b16 v[134:135], v120 offset:26304
	ds_read_b64_tr_b16 v[136:137], v120 offset:26336
	s_waitcnt vmcnt(1)
	s_waitcnt lgkmcnt(7)
	v_mfma_f32_16x16x16_bf16 v[28:31], v[122:123], v[116:117], v[28:31]
	s_waitcnt lgkmcnt(6)
	v_mfma_f32_16x16x16_bf16 v[24:27], v[124:125], v[116:117], v[24:27]
	s_waitcnt lgkmcnt(5)
	v_mfma_f32_16x16x16_bf16 v[20:23], v[126:127], v[116:117], v[20:23]
	s_waitcnt lgkmcnt(4)
	v_mfma_f32_16x16x16_bf16 v[16:19], v[128:129], v[116:117], v[16:19]
	s_waitcnt lgkmcnt(3)
	v_mfma_f32_16x16x16_bf16 v[12:15], v[130:131], v[116:117], v[12:15]
	s_waitcnt lgkmcnt(2)
	v_mfma_f32_16x16x16_bf16 v[8:11], v[132:133], v[116:117], v[8:11]
	s_waitcnt lgkmcnt(1)
	v_mfma_f32_16x16x16_bf16 v[4:7], v[134:135], v[116:117], v[4:7]
	s_waitcnt lgkmcnt(0)
	v_mfma_f32_16x16x16_bf16 v[0:3], v[136:137], v[116:117], v[0:3]
	s_cmp_eq_u32 s2, 7
	s_cbranch_scc1 .LBB0_949
	ds_read_b64_tr_b16 v[122:123], v120 offset:30464
	ds_read_b64_tr_b16 v[124:125], v120 offset:30496
	ds_read_b64_tr_b16 v[126:127], v120 offset:30528
	ds_read_b64_tr_b16 v[128:129], v120 offset:30560
	ds_read_b64_tr_b16 v[130:131], v120 offset:30592
	ds_read_b64_tr_b16 v[132:133], v120 offset:30624
	ds_read_b64_tr_b16 v[134:135], v120 offset:30656
	ds_read_b64_tr_b16 v[136:137], v120 offset:30688
	s_waitcnt vmcnt(0)
	s_waitcnt lgkmcnt(7)
	v_mfma_f32_16x16x16_bf16 v[28:31], v[122:123], v[118:119], v[28:31]
	s_waitcnt lgkmcnt(6)
	v_mfma_f32_16x16x16_bf16 v[24:27], v[124:125], v[118:119], v[24:27]
	s_waitcnt lgkmcnt(5)
	v_mfma_f32_16x16x16_bf16 v[20:23], v[126:127], v[118:119], v[20:23]
	s_waitcnt lgkmcnt(4)
	v_mfma_f32_16x16x16_bf16 v[16:19], v[128:129], v[118:119], v[16:19]
	s_waitcnt lgkmcnt(3)
	v_mfma_f32_16x16x16_bf16 v[12:15], v[130:131], v[118:119], v[12:15]
	s_waitcnt lgkmcnt(2)
	v_mfma_f32_16x16x16_bf16 v[8:11], v[132:133], v[118:119], v[8:11]
	s_waitcnt lgkmcnt(1)
	v_mfma_f32_16x16x16_bf16 v[4:7], v[134:135], v[118:119], v[4:7]
	s_waitcnt lgkmcnt(0)
	v_mfma_f32_16x16x16_bf16 v[0:3], v[136:137], v[118:119], v[0:3]
	s_branch .LBB0_949
